# speedup vs baseline: 1.0114x; 1.0014x over previous
; #define PG8_STAGE(bufoff, gbase, voff) do { _Pragma("unroll") for (int _i = 0; _i < 2; ++_i) \
;         __builtin_amdgcn_global_load_lds((const unsigned*)((const char*)(gbase) + (voff)[_i]), (PG8_LAS unsigned*)(lds + (bufoff) + ldsw + _i * 8192), 16, 0, 0); } while (0)
; #define PG8_LDA(dst, b, h) do { _Pragma("unroll") for (int m = 0; m < 4; ++m) _Pragma("unroll") for (int k = 0; k < 2; ++k) dst[m][k] = *(const PG8_LAS bf16x8*)(lds + PG8_SA(b, h) + aoff + m * 2048 + k * 1024); } while (0)
; #define PG8_LDB(dst, b, h) do { _Pragma("unroll") for (int n = 0; n < 2; ++n) _Pragma("unroll") for (int k = 0; k < 2; ++k) dst[n][k] = *(const PG8_LAS bf16x8*)(lds + PG8_SB(b, h) + boff + n * 2048 + k * 1024); } while (0)
; #define PG8_SCHED __builtin_amdgcn_sched_barrier(0)
;     __host__ __device__ bool next(int i, Unit& u) const {
;         const long L = (long)i * G + c; if (L >= nwg) return false;
;         int wgid = (int)L; { const int q = nwg / NXCD, r = nwg % NXCD, xcd = wgid % NXCD, off = wgid / NXCD; wgid = (xcd < r ? xcd * (q + 1) : r * (q + 1) + (xcd - r) * q) + off; }
;         const int nig = WGM * nN, gid = wgid / nig, fm = gid * WGM, gsz = (nM - fm) < WGM ? (nM - fm) : WGM;
;         u.pm = fm + ((wgid % nig) % gsz); u.pn = (wgid % nig) / gsz; return true;
;     }
; template <class Epi, class Sched, bool ALIGN_EPI = false, bool SP2 = false>
; __device__ __forceinline__ void gemm_phase(PG8_LAS unsigned char* lds, const Gemm g, const Sched& S, const Epi& E) {
;     ...
;         const bool has_next = S.next(ui + 1, nxt);
;         const char* nA = has_next ? (const char*)g.A + (size_t)nxt.pm * tstep : cA; const char* nB = has_next ? (const char*)g.Bt + (size_t)nxt.pn * tstep : cB;
;         for (int t = 0; t < nt; t += 2) {
;             const bool last = (t == nt - 2);
;             const char* a1 = cA + (size_t)(t + 1) * kstep;
;             const char* a2 = last ? nA : cA + (size_t)(t + 2) * kstep; const char* b2 = last ? nB : cB + (size_t)(t + 2) * kstep;
;             const char* a3 = a2 + kstep; const char* b3 = b2 + kstep;
;             if (last && has_next) S.a_ready(nxt);
;             if constexpr (SP2) {
;             PG8_LDB(B0, 0, 0); PG8_LDB(B1, 0, 1); PG8_SCHED; PG8_LDA(At, 0, 0); PG8_STAGE(PG8_SA(1, 1), a1 + hstep, voffA);
.LBB0_202:
	s_waitcnt vmcnt(16)
	s_waitcnt lgkmcnt(0)
	v_add_u32_e32 v204, 0x10000, v238
	ds_read_b128 v[80:83], v204
	ds_read_b128 v[88:91], v204 offset:1024
	ds_read_b128 v[104:107], v204 offset:2048
	ds_read_b128 v[108:111], v204 offset:3072
	ds_read_b128 v[128:131], v204 offset:16384
	ds_read_b128 v[132:135], v204 offset:17408
	ds_read_b128 v[152:155], v204 offset:18432
	ds_read_b128 v[156:159], v204 offset:19456
	ds_read_b128 v[160:163], v240
	ds_read_b128 v[164:167], v240 offset:1024
	ds_read_b128 v[168:171], v240 offset:2048
	ds_read_b128 v[172:175], v240 offset:3072
	ds_read_b128 v[176:179], v240 offset:4096
	ds_read_b128 v[180:183], v240 offset:5120
	ds_read_b128 v[184:187], v240 offset:6144
	ds_read_b128 v[200:203], v240 offset:7168
	s_add_i32 s81, s81, 1
	s_mul_i32 s3, s81, s86
	s_mul_hi_u32 s6, s81, s14
	s_add_i32 s6, s6, s3
	s_mul_i32 s3, s81, s14
	s_add_u32 s62, s3, s2
	s_addc_u32 s63, s6, s33
	v_mov_b64_e32 v[0:1], s[98:99]
	v_cmp_ge_i64_e32 vcc, s[62:63], v[0:1]
	v_cmp_lt_i64_e64 s[6:7], s[62:63], v[0:1]
	s_cbranch_vccnz .LBB0_204
	s_ashr_i32 s3, s62, 31
	s_lshr_b32 s3, s3, 29
	s_add_i32 s3, s62, s3
	s_ashr_i32 s9, s3, 3
	s_and_b32 s3, s3, -8
	s_sub_i32 s3, s62, s3
	s_lshr_b32 s36, s3, 31
	s_add_i32 s36, s15, s36
	s_mul_i32 s3, s36, s3
	s_add_i32 s3, s3, s9
	s_ashr_i32 s9, s3, 31
	s_lshr_b32 s9, s9, 26
	s_add_i32 s9, s3, s9
	s_ashr_i32 s36, s9, 6
	s_lshl_b32 s36, s36, 3
	s_sub_i32 s37, s15, s36
	s_min_i32 s37, s37, 8
	s_abs_i32 s38, s37
	v_cvt_f32_u32_e32 v0, s38
	s_sub_i32 s40, 0, s38
	s_andn2_b32 s9, s9, 63
	s_sub_i32 s3, s3, s9
	v_rcp_iflag_f32_e32 v0, v0
	s_abs_i32 s9, s3
	s_xor_b32 s39, s3, s37
	s_ashr_i32 s39, s39, 31
	v_mul_f32_e32 v0, 0x4f7ffffe, v0
	v_cvt_u32_f32_e32 v0, v0
	s_nop 0
	v_readfirstlane_b32 s41, v0
	s_mul_i32 s40, s40, s41
	s_mul_hi_u32 s40, s41, s40
	s_add_i32 s41, s41, s40
	s_mul_hi_u32 s40, s9, s41
	s_mul_i32 s41, s40, s38
	s_sub_i32 s9, s9, s41
	s_add_i32 s42, s40, 1
	s_sub_i32 s41, s9, s38
	s_cmp_ge_u32 s9, s38
	s_cselect_b32 s40, s42, s40
	s_cselect_b32 s9, s41, s9
	s_add_i32 s41, s40, 1
	s_cmp_ge_u32 s9, s38
	s_cselect_b32 s9, s41, s40
	s_xor_b32 s9, s9, s39
	s_sub_i32 s58, s9, s39
	s_mul_i32 s9, s58, s37
	s_sub_i32 s3, s3, s9
	s_add_i32 s60, s3, s36
